# grid barrier instances after the first: the never-taken first-use set-up path removed so the arrival code is straight-line (fewer instruction-cache misses on the barrier's critical path)
# baseline (speedup 1.0000x reference)
; __device__ __forceinline__ unsigned xb_add(unsigned* p, unsigned v) { return __hip_atomic_fetch_add(p, v, __ATOMIC_RELAXED, __HIP_MEMORY_SCOPE_AGENT); }
; __device__ __forceinline__ void xcd_barrier(const XcdBarrier& b) {
;     asm volatile("s_waitcnt vmcnt(0)" ::: "memory");
;     __syncthreads();
;     if (threadIdx.x == 0) {
;         unsigned* bar = b.bar;
;         __builtin_amdgcn_s_waitcnt(0);
;         unsigned nloc = b.st[0], nx = b.st[1];
;         if (nloc == 0u) { xcd_barrier_complete(bar, b.x, nloc, nx); b.st[0] = nloc; b.st[1] = nx; }
;         const unsigned old = xb_add(&bar[XB_XSUB(b.x)], 1u);
;         const unsigned gen = old / nloc;
;         if (old + 1u == (gen + 1u) * nloc) {
;             __builtin_amdgcn_fence(__ATOMIC_RELEASE, "agent");
;             asm volatile("s_waitcnt vmcnt(0)" ::: "memory");
;             const unsigned og = xb_add(&bar[XB_TOP], 1u);
;             const unsigned tg = og / nx;
;             if (og + 1u == (tg + 1u) * nx) xb_add(&bar[XB_TOPGEN], 1u);
.Lxbi1_skip:
	s_mov_b64 s[8:9], exec
	v_readlane_b32 s2, v254, 0
	v_readlane_b32 s3, v254, 1
	s_and_b64 s[2:3], s[8:9], s[2:3]
	s_mov_b64 exec, s[2:3]
	s_cbranch_execz .LBB0_505
	v_readlane_b32 s2, v254, 59
	s_waitcnt vmcnt(0) expcnt(0) lgkmcnt(0)
	s_nop 0
	v_mov_b32_e32 v0, s2
	ds_read_b32 v3, v0
	v_readlane_b32 s2, v254, 60
	s_waitcnt lgkmcnt(0)
	v_cmp_ne_u32_e32 vcc, 0, v3
	v_mov_b32_e32 v0, s2
	ds_read_b32 v2, v0
.LBB0_469:
	v_readlane_b32 s2, v254, 59
	v_readlane_b32 s3, v254, 60
	v_readlane_b32 s12, v254, 41
	v_readlane_b32 s13, v254, 42
	s_waitcnt lgkmcnt(0)
	v_mov_b32_e32 v0, s2
	v_mov_b32_e32 v4, s3
	ds_read_b32 v3, v0
	ds_read_b32 v2, v4
	v_mov_b32_e32 v5, 0
	v_mov_b32_e32 v6, 1
	s_nop 1
	global_atomic_add v6, v5, v6, s[12:13] sc0
	v_readlane_b32 s2, v254, 45
	v_readlane_b32 s3, v254, 46
	s_waitcnt vmcnt(0) lgkmcnt(0)
	v_cvt_f32_u32_e32 v0, v3
	v_sub_u32_e32 v4, 0, v3
	v_rcp_iflag_f32_e32 v0, v0
	s_nop 0
	v_mul_f32_e32 v0, 0x4f7ffffe, v0
	v_cvt_u32_f32_e32 v0, v0
	v_mul_lo_u32 v4, v4, v0
	v_mul_hi_u32 v4, v0, v4
	v_add_u32_e32 v0, v0, v4
	v_mul_hi_u32 v0, v6, v0
	v_mul_lo_u32 v4, v0, v3
	v_sub_u32_e32 v4, v6, v4
	v_add_u32_e32 v7, 1, v0
	v_cmp_ge_u32_e32 vcc, v4, v3
	s_nop 1
	v_cndmask_b32_e32 v0, v0, v7, vcc
	v_sub_u32_e32 v7, v4, v3
	v_cndmask_b32_e32 v4, v4, v7, vcc
	v_add_u32_e32 v7, 1, v0
	v_cmp_ge_u32_e32 vcc, v4, v3
	s_nop 1
	v_cndmask_b32_e32 v0, v0, v7, vcc
	v_add_u32_e32 v7, 1, v0
	v_mul_lo_u32 v4, v7, v3
	v_mul_lo_u32 v7, v7, v2
	v_add_u32_e32 v6, 1, v6
	v_cmp_ne_u32_e32 vcc, v6, v4
	s_mov_b32 s98, 0
	s_cbranch_vccnz .Lxb1_early
	s_nop 0
	buffer_wbl2 sc1
	s_waitcnt vmcnt(0)
	v_mov_b32_e32 v6, 1
	global_atomic_add v5, v6, s[2:3]
	s_branch .Lxb1_early

; __device__ __forceinline__ unsigned xb_add(unsigned* p, unsigned v) { return __hip_atomic_fetch_add(p, v, __ATOMIC_RELAXED, __HIP_MEMORY_SCOPE_AGENT); }
; __device__ __forceinline__ void xcd_barrier(const XcdBarrier& b) {
;     asm volatile("s_waitcnt vmcnt(0)" ::: "memory");
;     __syncthreads();
;     if (threadIdx.x == 0) {
;         unsigned* bar = b.bar;
;         __builtin_amdgcn_s_waitcnt(0);
;         unsigned nloc = b.st[0], nx = b.st[1];
;         if (nloc == 0u) { xcd_barrier_complete(bar, b.x, nloc, nx); b.st[0] = nloc; b.st[1] = nx; }
;         const unsigned old = xb_add(&bar[XB_XSUB(b.x)], 1u);
;         const unsigned gen = old / nloc;
;         if (old + 1u == (gen + 1u) * nloc) {
;             __builtin_amdgcn_fence(__ATOMIC_RELEASE, "agent");
;             asm volatile("s_waitcnt vmcnt(0)" ::: "memory");
;             const unsigned og = xb_add(&bar[XB_TOP], 1u);
;             const unsigned tg = og / nx;
;             if (og + 1u == (tg + 1u) * nx) xb_add(&bar[XB_TOPGEN], 1u);
.Lxbi2_skip:
	s_mov_b64 s[8:9], exec
	v_readlane_b32 s2, v254, 0
	v_readlane_b32 s3, v254, 1
	s_and_b64 s[2:3], s[8:9], s[2:3]
	s_mov_b64 exec, s[2:3]
	s_cbranch_execz .LBB0_677
	v_readlane_b32 s2, v254, 59
	s_waitcnt vmcnt(0) expcnt(0) lgkmcnt(0)
	s_nop 0
	v_mov_b32_e32 v0, s2
	ds_read_b32 v3, v0
	v_readlane_b32 s2, v254, 60
	s_waitcnt lgkmcnt(0)
	v_cmp_ne_u32_e32 vcc, 0, v3
	v_mov_b32_e32 v0, s2
	ds_read_b32 v2, v0
.LBB0_641:
	v_readlane_b32 s2, v254, 59
	v_readlane_b32 s3, v254, 60
	v_readlane_b32 s12, v254, 41
	v_readlane_b32 s13, v254, 42
	s_waitcnt lgkmcnt(0)
	v_mov_b32_e32 v0, s2
	v_mov_b32_e32 v4, s3
	ds_read_b32 v3, v0
	ds_read_b32 v2, v4
	v_mov_b32_e32 v5, 0
	v_mov_b32_e32 v6, 1
	s_nop 1
	global_atomic_add v6, v5, v6, s[12:13] sc0
	v_readlane_b32 s2, v254, 45
	v_readlane_b32 s3, v254, 46
	s_waitcnt vmcnt(0) lgkmcnt(0)
	v_cvt_f32_u32_e32 v0, v3
	v_sub_u32_e32 v4, 0, v3
	v_rcp_iflag_f32_e32 v0, v0
	s_nop 0
	v_mul_f32_e32 v0, 0x4f7ffffe, v0
	v_cvt_u32_f32_e32 v0, v0
	v_mul_lo_u32 v4, v4, v0
	v_mul_hi_u32 v4, v0, v4
	v_add_u32_e32 v0, v0, v4
	v_mul_hi_u32 v0, v6, v0
	v_mul_lo_u32 v4, v0, v3
	v_sub_u32_e32 v4, v6, v4
	v_add_u32_e32 v7, 1, v0
	v_cmp_ge_u32_e32 vcc, v4, v3
	s_nop 1
	v_cndmask_b32_e32 v0, v0, v7, vcc
	v_sub_u32_e32 v7, v4, v3
	v_cndmask_b32_e32 v4, v4, v7, vcc
	v_add_u32_e32 v7, 1, v0
	v_cmp_ge_u32_e32 vcc, v4, v3
	s_nop 1
	v_cndmask_b32_e32 v0, v0, v7, vcc
	v_add_u32_e32 v7, 1, v0
	v_mul_lo_u32 v4, v7, v3
	v_mul_lo_u32 v7, v7, v2
	v_add_u32_e32 v6, 1, v6
	v_cmp_ne_u32_e32 vcc, v6, v4
	s_mov_b32 s98, 0
	s_cbranch_vccnz .Lxb2_early
	s_nop 0
	buffer_wbl2 sc1
	s_waitcnt vmcnt(0)
	v_mov_b32_e32 v6, 1
	global_atomic_add v5, v6, s[2:3]
	s_branch .Lxb2_early

; __device__ __forceinline__ unsigned xb_add(unsigned* p, unsigned v) { return __hip_atomic_fetch_add(p, v, __ATOMIC_RELAXED, __HIP_MEMORY_SCOPE_AGENT); }
; __device__ __forceinline__ void xcd_barrier(const XcdBarrier& b) {
;     asm volatile("s_waitcnt vmcnt(0)" ::: "memory");
;     __syncthreads();
;     if (threadIdx.x == 0) {
;         unsigned* bar = b.bar;
;         __builtin_amdgcn_s_waitcnt(0);
;         unsigned nloc = b.st[0], nx = b.st[1];
;         if (nloc == 0u) { xcd_barrier_complete(bar, b.x, nloc, nx); b.st[0] = nloc; b.st[1] = nx; }
;         const unsigned old = xb_add(&bar[XB_XSUB(b.x)], 1u);
;         const unsigned gen = old / nloc;
;         if (old + 1u == (gen + 1u) * nloc) {
;             __builtin_amdgcn_fence(__ATOMIC_RELEASE, "agent");
;             asm volatile("s_waitcnt vmcnt(0)" ::: "memory");
;             const unsigned og = xb_add(&bar[XB_TOP], 1u);
;             const unsigned tg = og / nx;
;             if (og + 1u == (tg + 1u) * nx) xb_add(&bar[XB_TOPGEN], 1u);
.Lxbi3_skip:
	s_mov_b64 s[8:9], exec
	v_readlane_b32 s2, v254, 0
	v_readlane_b32 s3, v254, 1
	s_and_b64 s[2:3], s[8:9], s[2:3]
	s_mov_b64 exec, s[2:3]
	s_cbranch_execz .LBB0_777
	v_readlane_b32 s2, v254, 59
	s_waitcnt vmcnt(0) expcnt(0) lgkmcnt(0)
	s_nop 0
	v_mov_b32_e32 v0, s2
	ds_read_b32 v3, v0
	v_readlane_b32 s2, v254, 60
	s_waitcnt lgkmcnt(0)
	v_cmp_ne_u32_e32 vcc, 0, v3
	v_mov_b32_e32 v0, s2
	ds_read_b32 v2, v0
.LBB0_741:
	v_readlane_b32 s2, v254, 59
	v_readlane_b32 s3, v254, 60
	v_readlane_b32 s12, v254, 41
	v_readlane_b32 s13, v254, 42
	s_waitcnt lgkmcnt(0)
	v_mov_b32_e32 v0, s2
	v_mov_b32_e32 v4, s3
	ds_read_b32 v3, v0
	ds_read_b32 v2, v4
	v_mov_b32_e32 v5, 0
	v_mov_b32_e32 v6, 1
	s_nop 1
	global_atomic_add v6, v5, v6, s[12:13] sc0
	v_readlane_b32 s2, v254, 45
	v_readlane_b32 s3, v254, 46
	s_waitcnt vmcnt(0) lgkmcnt(0)
	v_cvt_f32_u32_e32 v0, v3
	v_sub_u32_e32 v4, 0, v3
	v_rcp_iflag_f32_e32 v0, v0
	s_nop 0
	v_mul_f32_e32 v0, 0x4f7ffffe, v0
	v_cvt_u32_f32_e32 v0, v0
	v_mul_lo_u32 v4, v4, v0
	v_mul_hi_u32 v4, v0, v4
	v_add_u32_e32 v0, v0, v4
	v_mul_hi_u32 v0, v6, v0
	v_mul_lo_u32 v4, v0, v3
	v_sub_u32_e32 v4, v6, v4
	v_add_u32_e32 v7, 1, v0
	v_cmp_ge_u32_e32 vcc, v4, v3
	s_nop 1
	v_cndmask_b32_e32 v0, v0, v7, vcc
	v_sub_u32_e32 v7, v4, v3
	v_cndmask_b32_e32 v4, v4, v7, vcc
	v_add_u32_e32 v7, 1, v0
	v_cmp_ge_u32_e32 vcc, v4, v3
	s_nop 1
	v_cndmask_b32_e32 v0, v0, v7, vcc
	v_add_u32_e32 v7, 1, v0
	v_mul_lo_u32 v4, v7, v3
	v_mul_lo_u32 v7, v7, v2
	v_add_u32_e32 v6, 1, v6
	v_cmp_ne_u32_e32 vcc, v6, v4
	s_mov_b32 s98, 0
	s_cbranch_vccnz .Lxb3_early
	s_nop 0
	buffer_wbl2 sc1
	s_waitcnt vmcnt(0)
	v_mov_b32_e32 v6, 1
	global_atomic_add v5, v6, s[2:3]
	s_branch .Lxb3_early

; __device__ __forceinline__ unsigned xb_add(unsigned* p, unsigned v) { return __hip_atomic_fetch_add(p, v, __ATOMIC_RELAXED, __HIP_MEMORY_SCOPE_AGENT); }
; __device__ __forceinline__ void xcd_barrier(const XcdBarrier& b) {
;     asm volatile("s_waitcnt vmcnt(0)" ::: "memory");
;     __syncthreads();
;     if (threadIdx.x == 0) {
;         unsigned* bar = b.bar;
;         __builtin_amdgcn_s_waitcnt(0);
;         unsigned nloc = b.st[0], nx = b.st[1];
;         if (nloc == 0u) { xcd_barrier_complete(bar, b.x, nloc, nx); b.st[0] = nloc; b.st[1] = nx; }
;         const unsigned old = xb_add(&bar[XB_XSUB(b.x)], 1u);
;         const unsigned gen = old / nloc;
;         if (old + 1u == (gen + 1u) * nloc) {
;             __builtin_amdgcn_fence(__ATOMIC_RELEASE, "agent");
;             asm volatile("s_waitcnt vmcnt(0)" ::: "memory");
;             const unsigned og = xb_add(&bar[XB_TOP], 1u);
;             const unsigned tg = og / nx;
;             if (og + 1u == (tg + 1u) * nx) xb_add(&bar[XB_TOPGEN], 1u);
.Lxbi4_skip:
	s_mov_b64 s[8:9], exec
	v_readlane_b32 s2, v254, 0
	v_readlane_b32 s3, v254, 1
	s_and_b64 s[2:3], s[8:9], s[2:3]
	s_mov_b64 exec, s[2:3]
	s_cbranch_execz .LBB0_969
	v_readlane_b32 s2, v254, 59
	s_waitcnt vmcnt(0) expcnt(0) lgkmcnt(0)
	s_nop 0
	v_mov_b32_e32 v0, s2
	ds_read_b32 v3, v0
	v_readlane_b32 s2, v254, 60
	s_waitcnt lgkmcnt(0)
	v_cmp_ne_u32_e32 vcc, 0, v3
	v_mov_b32_e32 v0, s2
	ds_read_b32 v2, v0
.LBB0_933:
	v_readlane_b32 s2, v254, 59
	v_readlane_b32 s3, v254, 60
	v_readlane_b32 s12, v254, 41
	v_readlane_b32 s13, v254, 42
	s_waitcnt lgkmcnt(0)
	v_mov_b32_e32 v0, s2
	v_mov_b32_e32 v4, s3
	ds_read_b32 v3, v0
	ds_read_b32 v2, v4
	v_mov_b32_e32 v5, 0
	v_mov_b32_e32 v6, 1
	s_nop 1
	global_atomic_add v6, v5, v6, s[12:13] sc0
	v_readlane_b32 s2, v254, 45
	v_readlane_b32 s3, v254, 46
	s_waitcnt vmcnt(0) lgkmcnt(0)
	v_cvt_f32_u32_e32 v0, v3
	v_sub_u32_e32 v4, 0, v3
	v_rcp_iflag_f32_e32 v0, v0
	s_nop 0
	v_mul_f32_e32 v0, 0x4f7ffffe, v0
	v_cvt_u32_f32_e32 v0, v0
	v_mul_lo_u32 v4, v4, v0
	v_mul_hi_u32 v4, v0, v4
	v_add_u32_e32 v0, v0, v4
	v_mul_hi_u32 v0, v6, v0
	v_mul_lo_u32 v4, v0, v3
	v_sub_u32_e32 v4, v6, v4
	v_add_u32_e32 v7, 1, v0
	v_cmp_ge_u32_e32 vcc, v4, v3
	s_nop 1
	v_cndmask_b32_e32 v0, v0, v7, vcc
	v_sub_u32_e32 v7, v4, v3
	v_cndmask_b32_e32 v4, v4, v7, vcc
	v_add_u32_e32 v7, 1, v0
	v_cmp_ge_u32_e32 vcc, v4, v3
	s_nop 1
	v_cndmask_b32_e32 v0, v0, v7, vcc
	v_add_u32_e32 v7, 1, v0
	v_mul_lo_u32 v4, v7, v3
	v_mul_lo_u32 v7, v7, v2
	v_add_u32_e32 v6, 1, v6
	v_cmp_ne_u32_e32 vcc, v6, v4
	s_mov_b32 s98, 0
	s_cbranch_vccnz .Lxb4_early
	s_nop 0
	buffer_wbl2 sc1
	s_waitcnt vmcnt(0)
	v_mov_b32_e32 v6, 1
	global_atomic_add v5, v6, s[2:3]
	s_branch .Lxb4_early

; __device__ __forceinline__ unsigned xb_add(unsigned* p, unsigned v) { return __hip_atomic_fetch_add(p, v, __ATOMIC_RELAXED, __HIP_MEMORY_SCOPE_AGENT); }
; __device__ __forceinline__ void xcd_barrier(const XcdBarrier& b) {
;     asm volatile("s_waitcnt vmcnt(0)" ::: "memory");
;     __syncthreads();
;     if (threadIdx.x == 0) {
;         unsigned* bar = b.bar;
;         __builtin_amdgcn_s_waitcnt(0);
;         unsigned nloc = b.st[0], nx = b.st[1];
;         if (nloc == 0u) { xcd_barrier_complete(bar, b.x, nloc, nx); b.st[0] = nloc; b.st[1] = nx; }
;         const unsigned old = xb_add(&bar[XB_XSUB(b.x)], 1u);
;         const unsigned gen = old / nloc;
;         if (old + 1u == (gen + 1u) * nloc) {
;             __builtin_amdgcn_fence(__ATOMIC_RELEASE, "agent");
;             asm volatile("s_waitcnt vmcnt(0)" ::: "memory");
;             const unsigned og = xb_add(&bar[XB_TOP], 1u);
;             const unsigned tg = og / nx;
;             if (og + 1u == (tg + 1u) * nx) xb_add(&bar[XB_TOPGEN], 1u);
.Lxbi5_skip:
	s_mov_b64 s[8:9], exec
	v_readlane_b32 s2, v254, 0
	v_readlane_b32 s3, v254, 1
	s_and_b64 s[2:3], s[8:9], s[2:3]
	s_mov_b64 exec, s[2:3]
	s_cbranch_execz .LBB0_1112
	v_readlane_b32 s2, v254, 59
	s_waitcnt vmcnt(0) expcnt(0) lgkmcnt(0)
	s_nop 0
	v_mov_b32_e32 v0, s2
	ds_read_b32 v3, v0
	v_readlane_b32 s2, v254, 60
	s_waitcnt lgkmcnt(0)
	v_cmp_ne_u32_e32 vcc, 0, v3
	v_mov_b32_e32 v0, s2
	ds_read_b32 v2, v0
.LBB0_1076:
	v_readlane_b32 s2, v254, 59
	v_readlane_b32 s3, v254, 60
	v_readlane_b32 s12, v254, 41
	v_readlane_b32 s13, v254, 42
	s_waitcnt lgkmcnt(0)
	v_mov_b32_e32 v0, s2
	v_mov_b32_e32 v4, s3
	ds_read_b32 v3, v0
	ds_read_b32 v2, v4
	v_mov_b32_e32 v5, 0
	v_mov_b32_e32 v6, 1
	s_nop 1
	global_atomic_add v6, v5, v6, s[12:13] sc0
	v_readlane_b32 s2, v254, 45
	v_readlane_b32 s3, v254, 46
	s_waitcnt vmcnt(0) lgkmcnt(0)
	v_cvt_f32_u32_e32 v0, v3
	v_sub_u32_e32 v4, 0, v3
	v_rcp_iflag_f32_e32 v0, v0
	s_nop 0
	v_mul_f32_e32 v0, 0x4f7ffffe, v0
	v_cvt_u32_f32_e32 v0, v0
	v_mul_lo_u32 v4, v4, v0
	v_mul_hi_u32 v4, v0, v4
	v_add_u32_e32 v0, v0, v4
	v_mul_hi_u32 v0, v6, v0
	v_mul_lo_u32 v4, v0, v3
	v_sub_u32_e32 v4, v6, v4
	v_add_u32_e32 v7, 1, v0
	v_cmp_ge_u32_e32 vcc, v4, v3
	s_nop 1
	v_cndmask_b32_e32 v0, v0, v7, vcc
	v_sub_u32_e32 v7, v4, v3
	v_cndmask_b32_e32 v4, v4, v7, vcc
	v_add_u32_e32 v7, 1, v0
	v_cmp_ge_u32_e32 vcc, v4, v3
	s_nop 1
	v_cndmask_b32_e32 v0, v0, v7, vcc
	v_add_u32_e32 v7, 1, v0
	v_mul_lo_u32 v4, v7, v3
	v_mul_lo_u32 v7, v7, v2
	v_add_u32_e32 v6, 1, v6
	v_cmp_ne_u32_e32 vcc, v6, v4
	s_mov_b32 s98, 0
	s_cbranch_vccnz .Lxb5_early
	s_nop 0
	buffer_wbl2 sc1
	s_waitcnt vmcnt(0)
	v_mov_b32_e32 v6, 1
	global_atomic_add v5, v6, s[2:3]
	s_branch .Lxb5_early

; __device__ __forceinline__ unsigned xb_add(unsigned* p, unsigned v) { return __hip_atomic_fetch_add(p, v, __ATOMIC_RELAXED, __HIP_MEMORY_SCOPE_AGENT); }
; __device__ __forceinline__ void xcd_barrier(const XcdBarrier& b) {
;     asm volatile("s_waitcnt vmcnt(0)" ::: "memory");
;     __syncthreads();
;     if (threadIdx.x == 0) {
;         unsigned* bar = b.bar;
;         __builtin_amdgcn_s_waitcnt(0);
;         unsigned nloc = b.st[0], nx = b.st[1];
;         if (nloc == 0u) { xcd_barrier_complete(bar, b.x, nloc, nx); b.st[0] = nloc; b.st[1] = nx; }
;         const unsigned old = xb_add(&bar[XB_XSUB(b.x)], 1u);
;         const unsigned gen = old / nloc;
;         if (old + 1u == (gen + 1u) * nloc) {
;             __builtin_amdgcn_fence(__ATOMIC_RELEASE, "agent");
;             asm volatile("s_waitcnt vmcnt(0)" ::: "memory");
;             const unsigned og = xb_add(&bar[XB_TOP], 1u);
;             const unsigned tg = og / nx;
;             if (og + 1u == (tg + 1u) * nx) xb_add(&bar[XB_TOPGEN], 1u);
.Lxbi6_skip:
	s_mov_b64 s[8:9], exec
	v_readlane_b32 s2, v254, 0
	v_readlane_b32 s3, v254, 1
	s_and_b64 s[2:3], s[8:9], s[2:3]
	s_mov_b64 exec, s[2:3]
	s_cbranch_execz .LBB0_1178
	v_readlane_b32 s2, v254, 59
	s_waitcnt vmcnt(0) expcnt(0) lgkmcnt(0)
	s_nop 0
	v_mov_b32_e32 v0, s2
	ds_read_b32 v3, v0
	v_readlane_b32 s2, v254, 60
	s_waitcnt lgkmcnt(0)
	v_cmp_ne_u32_e32 vcc, 0, v3
	v_mov_b32_e32 v0, s2
	ds_read_b32 v2, v0
.LBB0_1142:
	v_readlane_b32 s2, v254, 59
	v_readlane_b32 s3, v254, 60
	v_readlane_b32 s12, v254, 41
	v_readlane_b32 s13, v254, 42
	s_waitcnt lgkmcnt(0)
	v_mov_b32_e32 v0, s2
	v_mov_b32_e32 v4, s3
	ds_read_b32 v3, v0
	ds_read_b32 v2, v4
	v_mov_b32_e32 v5, 0
	v_mov_b32_e32 v6, 1
	s_nop 1
	global_atomic_add v6, v5, v6, s[12:13] sc0
	v_readlane_b32 s2, v254, 45
	v_readlane_b32 s3, v254, 46
	s_waitcnt vmcnt(0) lgkmcnt(0)
	v_cvt_f32_u32_e32 v0, v3
	v_sub_u32_e32 v4, 0, v3
	v_rcp_iflag_f32_e32 v0, v0
	s_nop 0
	v_mul_f32_e32 v0, 0x4f7ffffe, v0
	v_cvt_u32_f32_e32 v0, v0
	v_mul_lo_u32 v4, v4, v0
	v_mul_hi_u32 v4, v0, v4
	v_add_u32_e32 v0, v0, v4
	v_mul_hi_u32 v0, v6, v0
	v_mul_lo_u32 v4, v0, v3
	v_sub_u32_e32 v4, v6, v4
	v_add_u32_e32 v7, 1, v0
	v_cmp_ge_u32_e32 vcc, v4, v3
	s_nop 1
	v_cndmask_b32_e32 v0, v0, v7, vcc
	v_sub_u32_e32 v7, v4, v3
	v_cndmask_b32_e32 v4, v4, v7, vcc
	v_add_u32_e32 v7, 1, v0
	v_cmp_ge_u32_e32 vcc, v4, v3
	s_nop 1
	v_cndmask_b32_e32 v0, v0, v7, vcc
	v_add_u32_e32 v7, 1, v0
	v_mul_lo_u32 v4, v7, v3
	v_mul_lo_u32 v7, v7, v2
	v_add_u32_e32 v6, 1, v6
	v_cmp_ne_u32_e32 vcc, v6, v4
	s_mov_b32 s98, 0
	s_cbranch_vccnz .Lxb6_early
	s_nop 0
	buffer_wbl2 sc1
	s_waitcnt vmcnt(0)
	v_mov_b32_e32 v6, 1
	global_atomic_add v5, v6, s[2:3]
	s_branch .Lxb6_early

; __device__ __forceinline__ unsigned xb_add(unsigned* p, unsigned v) { return __hip_atomic_fetch_add(p, v, __ATOMIC_RELAXED, __HIP_MEMORY_SCOPE_AGENT); }
; __device__ __forceinline__ void xcd_barrier(const XcdBarrier& b) {
;     asm volatile("s_waitcnt vmcnt(0)" ::: "memory");
;     __syncthreads();
;     if (threadIdx.x == 0) {
;         unsigned* bar = b.bar;
;         __builtin_amdgcn_s_waitcnt(0);
;         unsigned nloc = b.st[0], nx = b.st[1];
;         if (nloc == 0u) { xcd_barrier_complete(bar, b.x, nloc, nx); b.st[0] = nloc; b.st[1] = nx; }
;         const unsigned old = xb_add(&bar[XB_XSUB(b.x)], 1u);
;         const unsigned gen = old / nloc;
;         if (old + 1u == (gen + 1u) * nloc) {
;             __builtin_amdgcn_fence(__ATOMIC_RELEASE, "agent");
;             asm volatile("s_waitcnt vmcnt(0)" ::: "memory");
;             const unsigned og = xb_add(&bar[XB_TOP], 1u);
;             const unsigned tg = og / nx;
;             if (og + 1u == (tg + 1u) * nx) xb_add(&bar[XB_TOPGEN], 1u);
.Lxbi7_skip:
	s_mov_b64 s[8:9], exec
	v_readlane_b32 s2, v254, 0
	v_readlane_b32 s3, v254, 1
	s_and_b64 s[2:3], s[8:9], s[2:3]
	s_mov_b64 exec, s[2:3]
	s_cbranch_execz .LBB0_1233
	v_readlane_b32 s2, v254, 59
	s_waitcnt vmcnt(0) expcnt(0) lgkmcnt(0)
	s_nop 0
	v_mov_b32_e32 v0, s2
	ds_read_b32 v3, v0
	v_readlane_b32 s2, v254, 60
	s_waitcnt lgkmcnt(0)
	v_cmp_ne_u32_e32 vcc, 0, v3
	v_mov_b32_e32 v0, s2
	ds_read_b32 v2, v0
.LBB0_1197:
	v_readlane_b32 s2, v254, 59
	v_readlane_b32 s3, v254, 60
	v_readlane_b32 s12, v254, 41
	v_readlane_b32 s13, v254, 42
	s_waitcnt lgkmcnt(0)
	v_mov_b32_e32 v0, s2
	v_mov_b32_e32 v4, s3
	ds_read_b32 v3, v0
	ds_read_b32 v2, v4
	v_mov_b32_e32 v5, 0
	v_mov_b32_e32 v6, 1
	s_nop 1
	global_atomic_add v6, v5, v6, s[12:13] sc0
	v_readlane_b32 s2, v254, 45
	v_readlane_b32 s3, v254, 46
	s_waitcnt vmcnt(0) lgkmcnt(0)
	v_cvt_f32_u32_e32 v0, v3
	v_sub_u32_e32 v4, 0, v3
	v_rcp_iflag_f32_e32 v0, v0
	s_nop 0
	v_mul_f32_e32 v0, 0x4f7ffffe, v0
	v_cvt_u32_f32_e32 v0, v0
	v_mul_lo_u32 v4, v4, v0
	v_mul_hi_u32 v4, v0, v4
	v_add_u32_e32 v0, v0, v4
	v_mul_hi_u32 v0, v6, v0
	v_mul_lo_u32 v4, v0, v3
	v_sub_u32_e32 v4, v6, v4
	v_add_u32_e32 v7, 1, v0
	v_cmp_ge_u32_e32 vcc, v4, v3
	s_nop 1
	v_cndmask_b32_e32 v0, v0, v7, vcc
	v_sub_u32_e32 v7, v4, v3
	v_cndmask_b32_e32 v4, v4, v7, vcc
	v_add_u32_e32 v7, 1, v0
	v_cmp_ge_u32_e32 vcc, v4, v3
	s_nop 1
	v_cndmask_b32_e32 v0, v0, v7, vcc
	v_add_u32_e32 v7, 1, v0
	v_mul_lo_u32 v4, v7, v3
	v_mul_lo_u32 v7, v7, v2
	v_add_u32_e32 v6, 1, v6
	v_cmp_ne_u32_e32 vcc, v6, v4
	s_mov_b32 s98, 0
	s_cbranch_vccnz .Lxb7_early
	s_nop 0
	buffer_wbl2 sc1
	s_waitcnt vmcnt(0)
	v_mov_b32_e32 v6, 1
	global_atomic_add v5, v6, s[2:3]
	s_branch .Lxb7_early

; __device__ __forceinline__ unsigned xb_add(unsigned* p, unsigned v) { return __hip_atomic_fetch_add(p, v, __ATOMIC_RELAXED, __HIP_MEMORY_SCOPE_AGENT); }
; __device__ __forceinline__ void xcd_barrier(const XcdBarrier& b) {
;     asm volatile("s_waitcnt vmcnt(0)" ::: "memory");
;     __syncthreads();
;     if (threadIdx.x == 0) {
;         unsigned* bar = b.bar;
;         __builtin_amdgcn_s_waitcnt(0);
;         unsigned nloc = b.st[0], nx = b.st[1];
;         if (nloc == 0u) { xcd_barrier_complete(bar, b.x, nloc, nx); b.st[0] = nloc; b.st[1] = nx; }
;         const unsigned old = xb_add(&bar[XB_XSUB(b.x)], 1u);
;         const unsigned gen = old / nloc;
;         if (old + 1u == (gen + 1u) * nloc) {
;             __builtin_amdgcn_fence(__ATOMIC_RELEASE, "agent");
;             asm volatile("s_waitcnt vmcnt(0)" ::: "memory");
;             const unsigned og = xb_add(&bar[XB_TOP], 1u);
;             const unsigned tg = og / nx;
;             if (og + 1u == (tg + 1u) * nx) xb_add(&bar[XB_TOPGEN], 1u);
.Lxbi8_skip:
	s_mov_b64 s[8:9], exec
	v_readlane_b32 s2, v254, 0
	v_readlane_b32 s3, v254, 1
	s_and_b64 s[2:3], s[8:9], s[2:3]
	s_mov_b64 exec, s[2:3]
	s_cbranch_execz .LBB0_1327
	v_readlane_b32 s2, v254, 59
	s_waitcnt vmcnt(0) expcnt(0) lgkmcnt(0)
	s_nop 0
	v_mov_b32_e32 v0, s2
	ds_read_b32 v3, v0
	v_readlane_b32 s2, v254, 60
	s_waitcnt lgkmcnt(0)
	v_cmp_ne_u32_e32 vcc, 0, v3
	v_mov_b32_e32 v0, s2
	ds_read_b32 v2, v0
.LBB0_1291:
	v_readlane_b32 s2, v254, 59
	v_readlane_b32 s3, v254, 60
	v_readlane_b32 s12, v254, 41
	v_readlane_b32 s13, v254, 42
	s_waitcnt lgkmcnt(0)
	v_mov_b32_e32 v0, s2
	v_mov_b32_e32 v4, s3
	ds_read_b32 v3, v0
	ds_read_b32 v2, v4
	v_mov_b32_e32 v5, 0
	v_mov_b32_e32 v6, 1
	s_nop 1
	global_atomic_add v6, v5, v6, s[12:13] sc0
	v_readlane_b32 s2, v254, 45
	v_readlane_b32 s3, v254, 46
	s_waitcnt vmcnt(0) lgkmcnt(0)
	v_cvt_f32_u32_e32 v0, v3
	v_sub_u32_e32 v4, 0, v3
	v_rcp_iflag_f32_e32 v0, v0
	s_nop 0
	v_mul_f32_e32 v0, 0x4f7ffffe, v0
	v_cvt_u32_f32_e32 v0, v0
	v_mul_lo_u32 v4, v4, v0
	v_mul_hi_u32 v4, v0, v4
	v_add_u32_e32 v0, v0, v4
	v_mul_hi_u32 v0, v6, v0
	v_mul_lo_u32 v4, v0, v3
	v_sub_u32_e32 v4, v6, v4
	v_add_u32_e32 v7, 1, v0
	v_cmp_ge_u32_e32 vcc, v4, v3
	s_nop 1
	v_cndmask_b32_e32 v0, v0, v7, vcc
	v_sub_u32_e32 v7, v4, v3
	v_cndmask_b32_e32 v4, v4, v7, vcc
	v_add_u32_e32 v7, 1, v0
	v_cmp_ge_u32_e32 vcc, v4, v3
	s_nop 1
	v_cndmask_b32_e32 v0, v0, v7, vcc
	v_add_u32_e32 v7, 1, v0
	v_mul_lo_u32 v4, v7, v3
	v_mul_lo_u32 v7, v7, v2
	v_add_u32_e32 v6, 1, v6
	v_cmp_ne_u32_e32 vcc, v6, v4
	s_mov_b32 s98, 0
	s_cbranch_vccnz .Lxb8_early
	s_nop 0
	buffer_wbl2 sc1
	s_waitcnt vmcnt(0)
	v_mov_b32_e32 v6, 1
	global_atomic_add v5, v6, s[2:3]
	s_branch .Lxb8_early

; __device__ __forceinline__ unsigned xb_add(unsigned* p, unsigned v) { return __hip_atomic_fetch_add(p, v, __ATOMIC_RELAXED, __HIP_MEMORY_SCOPE_AGENT); }
; __device__ __forceinline__ void xcd_barrier(const XcdBarrier& b) {
;     asm volatile("s_waitcnt vmcnt(0)" ::: "memory");
;     __syncthreads();
;     if (threadIdx.x == 0) {
;         unsigned* bar = b.bar;
;         __builtin_amdgcn_s_waitcnt(0);
;         unsigned nloc = b.st[0], nx = b.st[1];
;         if (nloc == 0u) { xcd_barrier_complete(bar, b.x, nloc, nx); b.st[0] = nloc; b.st[1] = nx; }
;         const unsigned old = xb_add(&bar[XB_XSUB(b.x)], 1u);
;         const unsigned gen = old / nloc;
;         if (old + 1u == (gen + 1u) * nloc) {
;             __builtin_amdgcn_fence(__ATOMIC_RELEASE, "agent");
;             asm volatile("s_waitcnt vmcnt(0)" ::: "memory");
;             const unsigned og = xb_add(&bar[XB_TOP], 1u);
;             const unsigned tg = og / nx;
;             if (og + 1u == (tg + 1u) * nx) xb_add(&bar[XB_TOPGEN], 1u);
.Lxbi9_skip:
	s_mov_b64 s[8:9], exec
	v_readlane_b32 s2, v254, 0
	v_readlane_b32 s3, v254, 1
	s_and_b64 s[2:3], s[8:9], s[2:3]
	s_mov_b64 exec, s[2:3]
	s_cbranch_execz .LBB0_1403
	v_readlane_b32 s2, v254, 59
	s_waitcnt vmcnt(0) expcnt(0) lgkmcnt(0)
	s_nop 0
	v_mov_b32_e32 v0, s2
	ds_read_b32 v3, v0
	v_readlane_b32 s2, v254, 60
	s_waitcnt lgkmcnt(0)
	v_cmp_ne_u32_e32 vcc, 0, v3
	v_mov_b32_e32 v0, s2
	ds_read_b32 v2, v0
.LBB0_1367:
	v_readlane_b32 s2, v254, 59
	v_readlane_b32 s3, v254, 60
	v_readlane_b32 s12, v254, 41
	v_readlane_b32 s13, v254, 42
	s_waitcnt lgkmcnt(0)
	v_mov_b32_e32 v0, s2
	v_mov_b32_e32 v4, s3
	ds_read_b32 v3, v0
	ds_read_b32 v2, v4
	v_mov_b32_e32 v5, 0
	v_mov_b32_e32 v6, 1
	s_nop 1
	global_atomic_add v6, v5, v6, s[12:13] sc0
	v_readlane_b32 s2, v254, 45
	v_readlane_b32 s3, v254, 46
	s_waitcnt vmcnt(0) lgkmcnt(0)
	v_cvt_f32_u32_e32 v0, v3
	v_sub_u32_e32 v4, 0, v3
	v_rcp_iflag_f32_e32 v0, v0
	s_nop 0
	v_mul_f32_e32 v0, 0x4f7ffffe, v0
	v_cvt_u32_f32_e32 v0, v0
	v_mul_lo_u32 v4, v4, v0
	v_mul_hi_u32 v4, v0, v4
	v_add_u32_e32 v0, v0, v4
	v_mul_hi_u32 v0, v6, v0
	v_mul_lo_u32 v4, v0, v3
	v_sub_u32_e32 v4, v6, v4
	v_add_u32_e32 v7, 1, v0
	v_cmp_ge_u32_e32 vcc, v4, v3
	s_nop 1
	v_cndmask_b32_e32 v0, v0, v7, vcc
	v_sub_u32_e32 v7, v4, v3
	v_cndmask_b32_e32 v4, v4, v7, vcc
	v_add_u32_e32 v7, 1, v0
	v_cmp_ge_u32_e32 vcc, v4, v3
	s_nop 1
	v_cndmask_b32_e32 v0, v0, v7, vcc
	v_add_u32_e32 v7, 1, v0
	v_mul_lo_u32 v4, v7, v3
	v_mul_lo_u32 v7, v7, v2
	v_add_u32_e32 v6, 1, v6
	v_cmp_ne_u32_e32 vcc, v6, v4
	s_mov_b32 s98, 0
	s_cbranch_vccnz .Lxb9_early
	s_nop 0
	buffer_wbl2 sc1
	s_waitcnt vmcnt(0)
	v_mov_b32_e32 v6, 1
	global_atomic_add v5, v6, s[2:3]
	s_branch .Lxb9_early

; __device__ __forceinline__ unsigned xb_add(unsigned* p, unsigned v) { return __hip_atomic_fetch_add(p, v, __ATOMIC_RELAXED, __HIP_MEMORY_SCOPE_AGENT); }
; __device__ __forceinline__ void xcd_barrier(const XcdBarrier& b) {
;     asm volatile("s_waitcnt vmcnt(0)" ::: "memory");
;     __syncthreads();
;     if (threadIdx.x == 0) {
;         unsigned* bar = b.bar;
;         __builtin_amdgcn_s_waitcnt(0);
;         unsigned nloc = b.st[0], nx = b.st[1];
;         if (nloc == 0u) { xcd_barrier_complete(bar, b.x, nloc, nx); b.st[0] = nloc; b.st[1] = nx; }
;         const unsigned old = xb_add(&bar[XB_XSUB(b.x)], 1u);
;         const unsigned gen = old / nloc;
;         if (old + 1u == (gen + 1u) * nloc) {
;             __builtin_amdgcn_fence(__ATOMIC_RELEASE, "agent");
;             asm volatile("s_waitcnt vmcnt(0)" ::: "memory");
;             const unsigned og = xb_add(&bar[XB_TOP], 1u);
;             const unsigned tg = og / nx;
;             if (og + 1u == (tg + 1u) * nx) xb_add(&bar[XB_TOPGEN], 1u);
.LBB0_1446:
	v_readlane_b32 s2, v254, 59
	s_waitcnt vmcnt(0) expcnt(0) lgkmcnt(0)
	s_nop 0
	v_mov_b32_e32 v0, s2
	ds_read_b32 v3, v0
	v_readlane_b32 s2, v254, 60
	s_waitcnt lgkmcnt(0)
	v_cmp_ne_u32_e32 vcc, 0, v3
	v_mov_b32_e32 v0, s2
	ds_read_b32 v2, v0
.LBB0_1461:
	v_readlane_b32 s2, v254, 59
	v_readlane_b32 s3, v254, 60
	v_readlane_b32 s12, v254, 41
	v_readlane_b32 s13, v254, 42
	s_waitcnt lgkmcnt(0)
	v_mov_b32_e32 v0, s2
	v_mov_b32_e32 v4, s3
	ds_read_b32 v3, v0
	ds_read_b32 v2, v4
	v_mov_b32_e32 v5, 0
	v_mov_b32_e32 v6, 1
	s_nop 1
	global_atomic_add v6, v5, v6, s[12:13] sc0
	v_readlane_b32 s2, v254, 45
	v_readlane_b32 s3, v254, 46
	s_waitcnt vmcnt(0) lgkmcnt(0)
	v_cvt_f32_u32_e32 v0, v3
	v_sub_u32_e32 v4, 0, v3
	v_rcp_iflag_f32_e32 v0, v0
	s_nop 0
	v_mul_f32_e32 v0, 0x4f7ffffe, v0
	v_cvt_u32_f32_e32 v0, v0
	v_mul_lo_u32 v4, v4, v0
	v_mul_hi_u32 v4, v0, v4
	v_add_u32_e32 v0, v0, v4
	v_mul_hi_u32 v0, v6, v0
	v_mul_lo_u32 v4, v0, v3
	v_sub_u32_e32 v4, v6, v4
	v_add_u32_e32 v7, 1, v0
	v_cmp_ge_u32_e32 vcc, v4, v3
	s_nop 1
	v_cndmask_b32_e32 v0, v0, v7, vcc
	v_sub_u32_e32 v7, v4, v3
	v_cndmask_b32_e32 v4, v4, v7, vcc
	v_add_u32_e32 v7, 1, v0
	v_cmp_ge_u32_e32 vcc, v4, v3
	s_nop 1
	v_cndmask_b32_e32 v0, v0, v7, vcc
	v_add_u32_e32 v7, 1, v0
	v_mul_lo_u32 v4, v7, v3
	v_mul_lo_u32 v7, v7, v2
	v_add_u32_e32 v6, 1, v6
	v_cmp_ne_u32_e32 vcc, v6, v4
	s_mov_b32 s98, 0
	s_cbranch_vccnz .Lxb10_early
	s_nop 0
	buffer_wbl2 sc1
	s_waitcnt vmcnt(0)
	v_mov_b32_e32 v6, 1
	global_atomic_add v5, v6, s[2:3]
	s_branch .Lxb10_early
